# prompt memory-attention epilogue also widened to dwordx4 via permlane32_swap
# speedup vs baseline: 1.0102x; 1.0092x over previous
; template <int DQK, bool MLA, bool QREG = true>
; DI void attn_unit(LAS unsigned char* lds, const bf16_t* Q, int ldq, int nqv, const bf16_t* K1, int ldk1, const bf16_t* K2, const bf16_t* VT, int ldv,
;                   int ntiles, int lim, int nkeys, bf16_t* O, int ldo, int tid, int wid, int lane) {
;     ...
;     lrun += __shfl_xor(lrun, 32);
.LBB0_1369:
	ds_read2_b64 v[98:101], v234 offset1:2
	v_sub_f32_e32 v82, v82, v236
	v_sub_f32_e32 v83, v83, v236
	v_sub_f32_e32 v84, v84, v236
	v_sub_f32_e32 v85, v85, v236
	v_sub_f32_e32 v86, v86, v236
	v_sub_f32_e32 v87, v87, v236
	v_sub_f32_e32 v88, v88, v236
	v_sub_f32_e32 v89, v89, v236
	v_exp_f32_e32 v82, v82
	v_exp_f32_e32 v83, v83
	v_exp_f32_e32 v84, v84
	v_exp_f32_e32 v85, v85
	v_exp_f32_e32 v86, v86
	v_exp_f32_e32 v87, v87
	v_exp_f32_e32 v88, v88
	v_exp_f32_e32 v89, v89
	v_cvt_pk_bf16_f32 v102, v82, v83
	v_cvt_pk_bf16_f32 v103, v84, v85
	v_cvt_pk_bf16_f32 v104, v86, v87
	v_cvt_pk_bf16_f32 v105, v88, v89
	v_sub_f32_e32 v90, v90, v236
	ds_read2_b64 v[106:109], v242 offset0:64 offset1:66
	s_waitcnt lgkmcnt(1)
	v_mfma_f32_32x32x16_bf16 v[18:33], v[98:101], v[102:105], v[18:33]
	ds_read2_b64 v[98:101], v241 offset0:32 offset1:34
	v_exp_f32_e32 v110, v90
	v_sub_f32_e32 v90, v91, v236
	v_exp_f32_e32 v111, v90
	v_sub_f32_e32 v90, v92, v236
	v_exp_f32_e32 v112, v90
	v_sub_f32_e32 v94, v94, v236
	s_waitcnt lgkmcnt(0)
	v_mfma_f32_32x32x16_bf16 v[34:49], v[98:101], v[102:105], v[34:49]
	v_sub_f32_e32 v98, v93, v236
	ds_read2_b64 v[90:93], v243 offset0:96 offset1:98
	v_sub_f32_e32 v66, v66, v236
	v_sub_f32_e32 v70, v70, v236
	v_sub_f32_e32 v74, v74, v236
	s_and_b64 vcc, exec, s[10:11]
	v_mfma_f32_32x32x16_bf16 v[2:17], v[106:109], v[102:105], v[2:17]
	v_exp_f32_e32 v106, v98
	v_exp_f32_e32 v107, v94
	v_sub_f32_e32 v94, v95, v236
	ds_read2_b64 v[98:101], v234 offset0:4 offset1:6
	v_exp_f32_e32 v108, v94
	v_sub_f32_e32 v94, v96, v236
	s_waitcnt lgkmcnt(1)
	v_mfma_f32_32x32x16_bf16 v[50:65], v[90:93], v[102:105], v[50:65]
	v_exp_f32_e32 v102, v94
	v_sub_f32_e32 v90, v97, v236
	ds_read2_b64 v[94:97], v241 offset0:36 offset1:38
	v_exp_f32_e32 v103, v90
	v_cvt_pk_bf16_f32 v90, v110, v111
	v_cvt_pk_bf16_f32 v91, v112, v106
	v_cvt_pk_bf16_f32 v92, v107, v108
	v_cvt_pk_bf16_f32 v93, v102, v103
	v_exp_f32_e32 v104, v66
	v_sub_f32_e32 v66, v67, v236
	s_waitcnt lgkmcnt(1)
	v_mfma_f32_32x32x16_bf16 v[18:33], v[98:101], v[90:93], v[18:33]
	ds_read2_b64 v[98:101], v242 offset0:68 offset1:70
	v_exp_f32_e32 v105, v66
	v_sub_f32_e32 v66, v68, v236
	v_exp_f32_e32 v109, v66
	v_add_f32_e32 v82, v82, v104
	s_waitcnt lgkmcnt(1)
	v_mfma_f32_32x32x16_bf16 v[34:49], v[94:97], v[90:93], v[34:49]
	v_sub_f32_e32 v94, v69, v236
	ds_read2_b64 v[66:69], v243 offset0:100 offset1:102
	s_waitcnt lgkmcnt(1)
	v_mfma_f32_32x32x16_bf16 v[2:17], v[98:101], v[90:93], v[2:17]
	v_exp_f32_e32 v99, v70
	v_sub_f32_e32 v70, v71, v236
	v_exp_f32_e32 v100, v70
	v_sub_f32_e32 v70, v72, v236
	v_exp_f32_e32 v101, v70
	v_exp_f32_e32 v98, v94
	ds_read2_b64 v[94:97], v234 offset0:8 offset1:10
	s_waitcnt lgkmcnt(1)
	v_mfma_f32_32x32x16_bf16 v[50:65], v[66:69], v[90:93], v[50:65]
	v_sub_f32_e32 v66, v73, v236
	ds_read2_b64 v[70:73], v241 offset0:40 offset1:42
	v_exp_f32_e32 v113, v66
	ds_read2_b64 v[90:93], v242 offset0:72 offset1:74
	v_cvt_pk_bf16_f32 v66, v104, v105
	v_cvt_pk_bf16_f32 v67, v109, v98
	v_cvt_pk_bf16_f32 v68, v99, v100
	v_cvt_pk_bf16_f32 v69, v101, v113
	s_waitcnt lgkmcnt(1)
	s_nop 0
	v_mfma_f32_32x32x16_bf16 v[34:49], v[70:73], v[66:69], v[34:49]
	v_sub_f32_e32 v70, v75, v236
	v_mfma_f32_32x32x16_bf16 v[18:33], v[94:97], v[66:69], v[18:33]
	v_exp_f32_e32 v95, v70
	v_sub_f32_e32 v70, v76, v236
	v_exp_f32_e32 v96, v70
	ds_read2_b64 v[70:73], v243 offset0:104 offset1:106
	v_exp_f32_e32 v94, v74
	v_sub_f32_e32 v74, v77, v236
	s_waitcnt lgkmcnt(1)
	v_mfma_f32_32x32x16_bf16 v[2:17], v[90:93], v[66:69], v[2:17]
	v_exp_f32_e32 v90, v74
	v_sub_f32_e32 v74, v78, v236
	v_exp_f32_e32 v91, v74
	v_sub_f32_e32 v74, v79, v236
	v_exp_f32_e32 v92, v74
	ds_read2_b64 v[74:77], v234 offset0:12 offset1:14
	v_sub_f32_e32 v78, v80, v236
	s_waitcnt lgkmcnt(1)
	v_mfma_f32_32x32x16_bf16 v[50:65], v[70:73], v[66:69], v[50:65]
	v_sub_f32_e32 v66, v81, v236
	v_exp_f32_e32 v93, v78
	v_exp_f32_e32 v97, v66
	v_cvt_pk_bf16_f32 v66, v94, v95
	v_cvt_pk_bf16_f32 v67, v96, v90
	v_cvt_pk_bf16_f32 v68, v91, v92
	v_cvt_pk_bf16_f32 v69, v93, v97
	s_waitcnt lgkmcnt(0)
	s_nop 0
	v_mfma_f32_32x32x16_bf16 v[18:33], v[74:77], v[66:69], v[18:33]
	ds_read2_b64 v[70:73], v241 offset0:44 offset1:46
	ds_read2_b64 v[74:77], v242 offset0:76 offset1:78
	ds_read2_b64 v[78:81], v243 offset0:108 offset1:110
	s_waitcnt lgkmcnt(0)
	s_barrier
	v_mfma_f32_32x32x16_bf16 v[34:49], v[70:73], v[66:69], v[34:49]
	v_add_f32_e32 v70, 0, v82
	v_add_f32_e32 v71, v83, v105
	v_add_f32_e32 v70, v71, v70
	v_add_f32_e32 v71, v84, v109
	v_add_f32_e32 v70, v71, v70
	v_add_f32_e32 v71, v85, v98
	v_add_f32_e32 v70, v71, v70
	v_add_f32_e32 v71, v86, v99
	v_add_f32_e32 v70, v71, v70
	v_add_f32_e32 v71, v87, v100
	v_add_f32_e32 v70, v71, v70
	v_add_f32_e32 v71, v88, v101
	v_add_f32_e32 v70, v71, v70
	v_add_f32_e32 v71, v89, v113
	v_mfma_f32_32x32x16_bf16 v[2:17], v[74:77], v[66:69], v[2:17]
	v_mfma_f32_32x32x16_bf16 v[50:65], v[78:81], v[66:69], v[50:65]
	v_add_f32_e32 v66, v71, v70
	v_add_f32_e32 v67, v110, v94
	v_add_f32_e32 v66, v67, v66
	v_add_f32_e32 v67, v111, v95
	v_add_f32_e32 v66, v67, v66
	v_add_f32_e32 v67, v112, v96
	v_add_f32_e32 v66, v67, v66
	v_add_f32_e32 v67, v106, v90
	v_add_f32_e32 v66, v67, v66
	v_add_f32_e32 v67, v107, v91
	v_add_f32_e32 v66, v67, v66
	v_add_f32_e32 v67, v108, v92
	v_add_f32_e32 v66, v67, v66
	v_add_f32_e32 v67, v102, v93
	v_add_f32_e32 v66, v67, v66
	v_add_f32_e32 v67, v103, v97
	v_add_f32_e32 v66, v67, v66
	v_add_f32_e32 v0, v0, v66
	ds_bpermute_b32 v66, v235, v0
	v_mbcnt_lo_u32_b32 v67, -1, 0
	v_mbcnt_hi_u32_b32 v67, -1, v67
	s_cbranch_vccnz .LBB0_1329
; DI unsigned pk2(float lo, float hi) { fv2 v = {lo, hi}; return __builtin_bit_cast(unsigned, __builtin_convertvector(v, bfv2)); }
; DI float rcpf(float x) { return __builtin_amdgcn_rcpf(x); }
; DI int lane_id() { int l; asm volatile("v_mbcnt_lo_u32_b32 %0, -1, 0\n\tv_mbcnt_hi_u32_b32 %0, -1, %0" : "=v"(l)); return l; }
; template <int DQK, bool MLA, bool QREG = true>
; DI void attn_unit(LAS unsigned char* lds, const bf16_t* Q, int ldq, int nqv, const bf16_t* K1, int ldk1, const bf16_t* K2, const bf16_t* VT, int ldv,
;                   int ntiles, int lim, int nkeys, bf16_t* O, int ldo, int tid, int wid, int lane) {
;     ...
;     lrun += __shfl_xor(lrun, 32);
;     const float il = rcpf(lrun);
;     const int t3 = lane_id();
;     const int qrow = wid * 32 + (t3 & 31), h3 = t3 >> 5;
;     if (lim > 0 && qrow < nqv) {
;         bf16_t* op = O + (size_t)qrow * ldo + 4 * h3;
; #pragma unroll
;         for (int v4 = 0; v4 < 4; ++v4)
; #pragma unroll
;             for (int g4 = 0; g4 < 4; ++g4) {
;                 u32x2 w; w.x = pk2(o[v4][4 * g4] * il, o[v4][4 * g4 + 1] * il); w.y = pk2(o[v4][4 * g4 + 2] * il, o[v4][4 * g4 + 3] * il);
;                 *(u32x2*)(op + 32 * v4 + 8 * g4) = w;
;             }
;     }
	s_lshl_b64 s[10:11], s[14:15], 11
	s_add_u32 s10, s19, s10
	s_addc_u32 s11, s20, s11
	s_add_u32 s10, s10, s24
	s_addc_u32 s11, s11, 0
	s_lshl_b32 s12, s25, 1
	s_waitcnt lgkmcnt(0)
	v_add_f32_e32 v0, v0, v66
	s_add_u32 s10, s10, s12
	v_rcp_f32_e32 v66, v0
	v_and_or_b32 v0, v67, 31, s86
	s_addc_u32 s11, s11, 0
	v_lshlrev_b32_e32 v0, 11, v0
	v_lshl_add_u64 v[68:69], s[10:11], 0, v[0:1]
	v_ashrrev_i32_e32 v0, 3, v67
	v_and_b32_e32 v70, -4, v0
	v_lshlrev_b32_e32 v70, 1, v70
	v_ashrrev_i32_e32 v71, 31, v70
	v_lshl_add_u64 v[68:69], v[70:71], 1, v[68:69]
	v_pk_mul_f32 v[100:101], v[18:19], v[66:67] op_sel_hi:[1,0]
	v_pk_mul_f32 v[102:103], v[20:21], v[66:67] op_sel_hi:[1,0]
	v_pk_mul_f32 v[104:105], v[22:23], v[66:67] op_sel_hi:[1,0]
	v_pk_mul_f32 v[106:107], v[24:25], v[66:67] op_sel_hi:[1,0]
	v_cvt_pk_bf16_f32 v108, v100, v101
	v_cvt_pk_bf16_f32 v109, v102, v103
	v_cvt_pk_bf16_f32 v110, v104, v105
	v_cvt_pk_bf16_f32 v111, v106, v107
	s_nop 1
	v_permlane32_swap_b32 v108, v110
	v_permlane32_swap_b32 v109, v111
	global_store_dwordx4 v[68:69], v[108:111], off
	s_nop 1
	v_pk_mul_f32 v[100:101], v[26:27], v[66:67] op_sel_hi:[1,0]
	v_pk_mul_f32 v[102:103], v[28:29], v[66:67] op_sel_hi:[1,0]
	v_pk_mul_f32 v[104:105], v[30:31], v[66:67] op_sel_hi:[1,0]
	v_pk_mul_f32 v[106:107], v[32:33], v[66:67] op_sel_hi:[1,0]
	v_cvt_pk_bf16_f32 v108, v100, v101
	v_cvt_pk_bf16_f32 v109, v102, v103
	v_cvt_pk_bf16_f32 v110, v104, v105
	v_cvt_pk_bf16_f32 v111, v106, v107
	s_nop 1
	v_permlane32_swap_b32 v108, v110
	v_permlane32_swap_b32 v109, v111
	global_store_dwordx4 v[68:69], v[108:111], off offset:32
	s_nop 1
	v_pk_mul_f32 v[100:101], v[34:35], v[66:67] op_sel_hi:[1,0]
	v_pk_mul_f32 v[102:103], v[36:37], v[66:67] op_sel_hi:[1,0]
	v_pk_mul_f32 v[104:105], v[38:39], v[66:67] op_sel_hi:[1,0]
	v_pk_mul_f32 v[106:107], v[40:41], v[66:67] op_sel_hi:[1,0]
	v_cvt_pk_bf16_f32 v108, v100, v101
	v_cvt_pk_bf16_f32 v109, v102, v103
	v_cvt_pk_bf16_f32 v110, v104, v105
	v_cvt_pk_bf16_f32 v111, v106, v107
	s_nop 1
	v_permlane32_swap_b32 v108, v110
	v_permlane32_swap_b32 v109, v111
	global_store_dwordx4 v[68:69], v[108:111], off offset:64
	s_nop 1
	v_pk_mul_f32 v[100:101], v[42:43], v[66:67] op_sel_hi:[1,0]
	v_pk_mul_f32 v[102:103], v[44:45], v[66:67] op_sel_hi:[1,0]
	v_pk_mul_f32 v[104:105], v[46:47], v[66:67] op_sel_hi:[1,0]
	v_pk_mul_f32 v[106:107], v[48:49], v[66:67] op_sel_hi:[1,0]
	v_cvt_pk_bf16_f32 v108, v100, v101
	v_cvt_pk_bf16_f32 v109, v102, v103
	v_cvt_pk_bf16_f32 v110, v104, v105
	v_cvt_pk_bf16_f32 v111, v106, v107
	s_nop 1
	v_permlane32_swap_b32 v108, v110
	v_permlane32_swap_b32 v109, v111
	global_store_dwordx4 v[68:69], v[108:111], off offset:96
	s_nop 1
	v_pk_mul_f32 v[100:101], v[2:3], v[66:67] op_sel_hi:[1,0]
	v_pk_mul_f32 v[102:103], v[4:5], v[66:67] op_sel_hi:[1,0]
	v_pk_mul_f32 v[104:105], v[6:7], v[66:67] op_sel_hi:[1,0]
	v_pk_mul_f32 v[106:107], v[8:9], v[66:67] op_sel_hi:[1,0]
	v_cvt_pk_bf16_f32 v108, v100, v101
	v_cvt_pk_bf16_f32 v109, v102, v103
	v_cvt_pk_bf16_f32 v110, v104, v105
	v_cvt_pk_bf16_f32 v111, v106, v107
	s_nop 1
	v_permlane32_swap_b32 v108, v110
	v_permlane32_swap_b32 v109, v111
	global_store_dwordx4 v[68:69], v[108:111], off offset:128
	s_nop 1
	v_pk_mul_f32 v[100:101], v[10:11], v[66:67] op_sel_hi:[1,0]
	v_pk_mul_f32 v[102:103], v[12:13], v[66:67] op_sel_hi:[1,0]
	v_pk_mul_f32 v[104:105], v[14:15], v[66:67] op_sel_hi:[1,0]
	v_pk_mul_f32 v[106:107], v[16:17], v[66:67] op_sel_hi:[1,0]
	v_cvt_pk_bf16_f32 v108, v100, v101
	v_cvt_pk_bf16_f32 v109, v102, v103
	v_cvt_pk_bf16_f32 v110, v104, v105
	v_cvt_pk_bf16_f32 v111, v106, v107
	s_nop 1
	v_permlane32_swap_b32 v108, v110
	v_permlane32_swap_b32 v109, v111
	global_store_dwordx4 v[68:69], v[108:111], off offset:160
	s_nop 1
	v_pk_mul_f32 v[100:101], v[50:51], v[66:67] op_sel_hi:[1,0]
	v_pk_mul_f32 v[102:103], v[52:53], v[66:67] op_sel_hi:[1,0]
	v_pk_mul_f32 v[104:105], v[54:55], v[66:67] op_sel_hi:[1,0]
	v_pk_mul_f32 v[106:107], v[56:57], v[66:67] op_sel_hi:[1,0]
	v_cvt_pk_bf16_f32 v108, v100, v101
	v_cvt_pk_bf16_f32 v109, v102, v103
	v_cvt_pk_bf16_f32 v110, v104, v105
	v_cvt_pk_bf16_f32 v111, v106, v107
	s_nop 1
	v_permlane32_swap_b32 v108, v110
	v_permlane32_swap_b32 v109, v111
	global_store_dwordx4 v[68:69], v[108:111], off offset:192
	s_nop 1
	v_pk_mul_f32 v[100:101], v[58:59], v[66:67] op_sel_hi:[1,0]
	v_pk_mul_f32 v[102:103], v[60:61], v[66:67] op_sel_hi:[1,0]
	v_pk_mul_f32 v[104:105], v[62:63], v[66:67] op_sel_hi:[1,0]
	v_pk_mul_f32 v[106:107], v[64:65], v[66:67] op_sel_hi:[1,0]
	v_cvt_pk_bf16_f32 v108, v100, v101
	v_cvt_pk_bf16_f32 v109, v102, v103
	v_cvt_pk_bf16_f32 v110, v104, v105
	v_cvt_pk_bf16_f32 v111, v106, v107
	s_nop 1
	v_permlane32_swap_b32 v108, v110
	v_permlane32_swap_b32 v109, v111
	global_store_dwordx4 v[68:69], v[108:111], off offset:224
	s_nop 1
	s_branch .LBB0_1329
